# latent attention unit prologue: K/V tiles 0 and 1 staged by LDS-DMA issued right behind the Q loads (two serial load->ds_write rounds removed)
# speedup vs baseline: 1.0116x; 1.0005x over previous
.LBB0_853:
	s_and_b64 vcc, exec, s[0:1]
	s_cbranch_vccz .LBB0_820
	s_ashr_i32 s14, s49, 5
	s_ashr_i32 s15, s14, 31
	s_lshl_b32 s0, s49, 8
	s_lshl_b64 s[42:43], s[14:15], 11
	s_and_b32 s0, s0, 0x700
	s_or_b32 s42, s42, s0
	s_mul_i32 s0, s43, 0x600
	s_mul_hi_u32 s1, s42, 0x600
	s_bfe_u32 s4, s49, 0x20003
	s_add_i32 s1, s1, s0
	s_mul_i32 s0, s42, 0x600
	s_add_u32 s0, s84, s0
	s_addc_u32 s1, s85, s1
	s_mul_i32 s2, s4, 0x180
	s_add_u32 s16, s0, s2
	s_addc_u32 s17, s1, 0
	v_readlane_b32 s0, v251, 48
	v_readlane_b32 s1, v251, 49
	s_add_u32 s2, s0, s2
	s_addc_u32 s8, s1, 0
	s_lshl_b32 s7, s4, 7
	s_lshl_b32 s0, s4, 8
	v_readlane_b32 s10, v253, 7
	v_mov_b32_e32 v170, v0
	v_readlane_b32 s11, v253, 8
	s_add_u32 s9, s10, s0
	s_addc_u32 s10, s11, 0
	v_ashrrev_i32_e32 v161, 6, v170
	v_and_b32_e32 v172, 31, v170
	v_and_b32_e32 v2, 0x3fffffc0, v170
	s_add_i32 s1, 0, 0x14000
	v_lshlrev_b32_e32 v160, 5, v161
	v_bfe_u32 v173, v170, 5, 1
	v_lshl_add_u32 v64, v2, 2, s1
	v_or_b32_e32 v4, v160, v172
	s_waitcnt lgkmcnt(0)
	v_mov_b64_e32 v[2:3], s[16:17]
	s_movk_i32 s11, 0x600
	v_mad_i64_i32 v[2:3], s[16:17], v4, s11, v[2:3]
	v_lshlrev_b32_e32 v62, 4, v173
	v_mov_b32_e32 v63, v99
	v_lshl_add_u64 v[6:7], v[2:3], 0, v[62:63]
	v_lshlrev_b32_e32 v2, 12, v161
	s_add_i32 s1, 0, 0x14800
	v_lshlrev_b32_e32 v3, 7, v172
	global_load_dwordx4 v[128:131], v[6:7], off
	global_load_dwordx4 v[124:127], v[6:7], off offset:32
	global_load_dwordx4 v[120:123], v[6:7], off offset:64
	global_load_dwordx4 v[116:119], v[6:7], off offset:96
	global_load_dwordx4 v[112:115], v[6:7], off offset:128
	global_load_dwordx4 v[108:111], v[6:7], off offset:160
	global_load_dwordx4 v[104:107], v[6:7], off offset:192
	global_load_dwordx4 v[100:103], v[6:7], off offset:224
	v_add3_u32 v51, s1, v2, v3
	global_load_dwordx4 v[2:5], v[6:7], off offset:256
	global_load_dwordx4 v[132:135], v[6:7], off offset:288
	global_load_dwordx4 v[136:139], v[6:7], off offset:320
	global_load_dwordx4 v[140:143], v[6:7], off offset:352
	v_bitop3_b32 v8, v173, v170, 7 bitop3:0x78
	v_lshl_add_u32 v8, v8, 4, v51
	v_lshlrev_b32_e32 v14, 4, v170
	v_and_b32_e32 v50, 0x70, v14
	s_movk_i32 s1, 0x60
	s_movk_i32 s18, 0x180
	s_lshl_b32 s12, s14, 8
	s_add_i32 s0, s12, 0x4000
	s_lshl_b32 s13, s14, 11
	s_cmp_lg_u32 0, -1
	s_mul_i32 s15, s14, 0x60000
	s_cselect_b32 s14, 0, 0
	s_mov_b32 s100, 0xaaaaaaab
	v_lshrrev_b32_e32 v38, 6, v0
	v_lshl_add_u32 v39, v38, 7, v0
	v_mul_hi_u32 v40, v39, s100
	v_lshrrev_b32_e32 v40, 4, v40
	v_mul_u32_u24_e32 v41, 24, v40
	v_sub_u32_e32 v41, v39, v41
	v_and_b32_e32 v42, 7, v40
	v_xor_b32_e32 v41, v41, v42
	v_mul_u32_u24_e32 v42, 0x600, v40
	v_lshl_add_u32 v180, v41, 4, v42
	v_add_u32_e32 v39, 64, v39
	v_mul_hi_u32 v40, v39, s100
	v_lshrrev_b32_e32 v40, 4, v40
	v_mul_u32_u24_e32 v41, 24, v40
	v_sub_u32_e32 v41, v39, v41
	v_and_b32_e32 v42, 7, v40
	v_xor_b32_e32 v41, v41, v42
	v_mul_u32_u24_e32 v42, 0x600, v40
	v_lshl_add_u32 v181, v41, 4, v42
	v_add_u32_e32 v39, 64, v39
	v_mul_hi_u32 v40, v39, s100
	v_lshrrev_b32_e32 v40, 4, v40
	v_mul_u32_u24_e32 v41, 24, v40
	v_sub_u32_e32 v41, v39, v41
	v_and_b32_e32 v42, 7, v40
	v_xor_b32_e32 v41, v41, v42
	v_mul_u32_u24_e32 v42, 0x600, v40
	v_lshl_add_u32 v182, v41, 4, v42
	v_lshl_add_u32 v39, v38, 6, v0
	v_and_b32_e32 v40, 3, v39
	v_lshlrev_b32_e32 v40, 4, v40
	v_bfe_u32 v41, v39, 5, 2
	v_lshl_or_b32 v40, v41, 6, v40
	v_bfe_u32 v41, v39, 2, 2
	v_lshl_or_b32 v40, v41, 10, v40
	v_bfe_u32 v41, v39, 7, 1
	v_lshl_or_b32 v40, v41, 12, v40
	v_bfe_u32 v41, v39, 4, 1
	v_lshl_or_b32 v40, v41, 13, v40
	v_bfe_u32 v41, v39, 8, 2
	v_lshl_or_b32 v178, v41, 14, v40
	v_add_u32_e32 v39, 64, v39
	v_and_b32_e32 v40, 3, v39
	v_lshlrev_b32_e32 v40, 4, v40
	v_bfe_u32 v41, v39, 5, 2
	v_lshl_or_b32 v40, v41, 6, v40
	v_bfe_u32 v41, v39, 2, 2
	v_lshl_or_b32 v40, v41, 10, v40
	v_bfe_u32 v41, v39, 7, 1
	v_lshl_or_b32 v40, v41, 12, v40
	v_bfe_u32 v41, v39, 4, 1
	v_lshl_or_b32 v40, v41, 13, v40
	v_bfe_u32 v41, v39, 8, 2
	v_lshl_or_b32 v179, v41, 14, v40
	v_readfirstlane_b32 s101, v38
	s_nop 1
	s_mul_i32 vcc_lo, s101, 0xc00
	s_lshl_b32 vcc_hi, s101, 11
	s_ashr_i32 s101, s0, 31
	s_mov_b32 s100, s0
	s_lshl_b64 s[16:17], s[100:101], 10
	s_add_u32 s16, s9, s16
	s_addc_u32 s17, s10, s17
	s_mul_hi_i32 s101, s0, 0x600
	s_add_i32 s100, s15, 0x1800000
	s_add_u32 s100, s2, s100
	s_addc_u32 s101, s8, s101
	s_add_i32 m0, vcc_hi, 0x0
	s_nop 0
	global_load_lds_dwordx4 v178, s[16:17]
	s_add_i32 m0, vcc_hi, 0x400
	s_nop 0
	global_load_lds_dwordx4 v179, s[16:17]
	s_add_i32 m0, vcc_lo, 0x8000
	s_nop 0
	global_load_lds_dwordx4 v180, s[100:101]
	s_add_i32 m0, vcc_lo, 0x8400
	s_nop 0
	global_load_lds_dwordx4 v181, s[100:101]
	s_add_i32 m0, vcc_lo, 0x8800
	s_nop 0
	global_load_lds_dwordx4 v182, s[100:101]
	s_add_u32 s16, s16, 0x10000
	s_addc_u32 s17, s17, 0
	s_add_u32 s100, s100, 0x18000
	s_addc_u32 s101, s101, 0
	s_add_i32 m0, vcc_hi, 0x4000
	s_nop 0
	global_load_lds_dwordx4 v178, s[16:17]
	s_add_i32 m0, vcc_hi, 0x4400
	s_nop 0
	global_load_lds_dwordx4 v179, s[16:17]
	s_add_i32 m0, vcc_lo, 0xe000
	s_nop 0
	global_load_lds_dwordx4 v180, s[100:101]
	s_add_i32 m0, vcc_lo, 0xe400
	s_nop 0
	global_load_lds_dwordx4 v181, s[100:101]
	s_add_i32 m0, vcc_lo, 0xe800
	s_nop 0
	global_load_lds_dwordx4 v182, s[100:101]
	s_mov_b32 s101, vcc_lo
	s_mov_b32 s100, vcc_hi
	v_and_b32_e32 v171, 63, v170
	v_mul_u32_u24_e32 v55, 0x180, v172
	v_or_b32_e32 v52, 32, v62
	v_bitop3_b32 v56, v52, v55, v50 bitop3:0xde
	v_add_u32_e32 v184, 0, v56
	v_or_b32_e32 v53, 64, v62
	v_or_b32_e32 v54, 0x60, v62
	s_mov_b32 s68, s69
	s_mov_b32 s70, s69
	s_mov_b32 s71, s69
	s_mov_b32 s72, s69
	s_mov_b32 s73, s69
	s_mov_b32 s74, s69
	s_mov_b32 s75, s69
	s_mov_b32 s76, s69
	s_mov_b32 s77, s69
	s_mov_b32 s78, s69
	s_mov_b32 s79, s69
	s_mov_b32 s80, s69
	s_mov_b32 s81, s69
	s_mov_b32 s82, s69
	s_mov_b32 s83, s69
	v_lshl_add_u32 v197, v172, 2, v64
	v_add_u32_e32 v193, v64, v62
	v_mov_b32_e32 v212, 0x358637bd
	v_mov_b32_e32 v200, 0xff
	v_mov_b32_e32 v202, 0x1b00
	v_mov_b32_e32 v201, 0x600
	v_mov_b32_e32 v203, 0x260
	v_mov_b32_e32 v169, v99
	v_mov_b32_e32 v163, v99
	v_mov_b32_e32 v165, v99
	v_mov_b32_e32 v167, v99
	v_cmp_gt_u32_e64 s[38:39], 32, v171
	v_mov_b32_e32 v198, 0
	s_waitcnt vmcnt(10)
	ds_write_b128 v8, v[2:5]
	v_bitop3_b32 v8, v62, v50, 32 bitop3:0x36
	v_add_u32_e32 v176, v51, v8
	v_bitop3_b32 v8, v62, v50, 64 bitop3:0x36
	v_add_u32_e32 v177, v51, v8
	ds_write_b128 v176, v[132:135]
	ds_write_b128 v177, v[136:139]
	v_bitop3_b32 v6, v62, v50, s1 bitop3:0x36
	v_add_u32_e32 v175, v51, v6
	s_mov_b32 s1, 0x2aaaaaab
	ds_write_b128 v175, v[140:143]
	v_ashrrev_i32_e32 v2, 4, v170
	v_and_b32_e32 v5, 0xfffff0, v2
	v_lshlrev_b32_e32 v6, 1, v2
	v_and_or_b32 v5, v6, 8, v5
	v_lshrrev_b32_e32 v6, 1, v2
	v_and_b32_e32 v7, 3, v2
	v_and_or_b32 v6, v6, 4, v7
	v_add_u32_e32 v7, 32, v2
	v_and_b32_e32 v8, 0xfffff0, v7
	v_lshlrev_b32_e32 v7, 1, v7
	v_lshlrev_b32_e32 v3, 3, v170
	v_and_or_b32 v7, v7, 8, v8
	v_and_b32_e32 v4, 0x78, v3
	v_lshrrev_b32_e32 v5, 1, v5
	v_bfe_u32 v3, v3, 5, 2
	v_lshrrev_b32_e32 v7, 1, v7
	v_or_b32_e32 v5, v5, v3
	v_or_b32_e32 v3, v7, v3
	v_mul_hi_i32 v7, v170, s1
	v_lshrrev_b32_e32 v8, 31, v7
	v_ashrrev_i32_e32 v7, 2, v7
	v_add_u32_e32 v7, v7, v8
	v_mul_lo_u32 v8, v7, 24
	v_sub_u32_e32 v8, v170, v8
	v_mul_lo_u32 v9, v7, s11
	v_lshl_add_u32 v162, v8, 4, v9
	v_mul_lo_u32 v9, v7, s18
	v_bitop3_b32 v7, v7, v8, 7 bitop3:0x6c
	v_lshl_add_u32 v15, v7, 4, v9
	v_add_u32_e32 v7, 0x200, v170
	v_mul_hi_i32 v8, v7, s1
	v_lshrrev_b32_e32 v9, 31, v8
	v_ashrrev_i32_e32 v8, 2, v8
	v_add_u32_e32 v8, v8, v9
	v_mul_lo_u32 v9, v8, 24
	v_sub_u32_e32 v7, v7, v9
	v_mul_lo_u32 v9, v8, s11
	v_lshl_add_u32 v164, v7, 4, v9
	v_mul_lo_u32 v9, v8, s18
	v_bitop3_b32 v7, v8, v7, 7 bitop3:0x6c
	v_lshl_add_u32 v24, v7, 4, v9
	v_add_u32_e32 v7, 0x400, v170
	v_mul_hi_i32 v8, v7, s1
	v_lshrrev_b32_e32 v9, 31, v8
	v_ashrrev_i32_e32 v8, 2, v8
	v_add_u32_e32 v8, v8, v9
	v_mul_lo_u32 v9, v8, 24
	v_sub_u32_e32 v7, v7, v9
	v_mul_lo_u32 v9, v8, s11
	v_lshlrev_b32_e32 v4, 1, v4
	v_lshl_add_u32 v166, v7, 4, v9
	v_mul_lo_u32 v9, v8, s18
	v_bitop3_b32 v7, v8, v7, 7 bitop3:0x6c
	s_ashr_i32 s1, s0, 31
	v_lshlrev_b32_e32 v6, 6, v6
	v_lshlrev_b32_e32 v3, 9, v3
	v_lshl_add_u32 v25, v7, 4, v9
	v_and_b32_e32 v7, 48, v4
	s_lshl_b64 s[16:17], s[0:1], 10
	v_or3_b32 v27, v3, v6, v7
	v_lshl_or_b32 v98, v2, 10, v4
	v_lshlrev_b32_e32 v2, 3, v171
	v_and_b32_e32 v3, 0xc0, v14
	v_lshlrev_b32_e32 v4, 1, v170
	s_add_u32 s16, s9, s16
	v_lshlrev_b32_e32 v5, 9, v5
	v_and_or_b32 v3, v2, 24, v3
	v_and_b32_e32 v4, 32, v4
	v_and_b32_e32 v2, 0x100, v2
	s_addc_u32 s17, s10, s17
	v_or3_b32 v26, v5, v6, v7
	v_or3_b32 v63, v3, v4, v2
	s_add_i32 s15, s15, 0x1800000
	s_mul_hi_i32 s1, s0, 0x600
	s_add_u32 s0, s2, s15
	v_add_u32_e32 v168, 0x8000, v98
	s_addc_u32 s1, s8, s1
	s_movk_i32 s0, 0x70
	v_bitop3_b32 v61, v62, v14, s0 bitop3:0x78
	s_movk_i32 s0, 0x80
	v_add_u32_e32 v192, v51, v61
	v_add_u32_e32 v174, s14, v63
	s_mov_b32 s11, -1
	v_mov_b32_e32 v2, 0x3000
	v_mad_u32_u24 v60, v172, s18, v2
	v_bitop3_b32 v2, v62, v55, v50 bitop3:0xde
	v_add_u32_e32 v183, 0, v2
	s_waitcnt vmcnt(5) lgkmcnt(0)
	s_barrier
	ds_read_b128 v[18:21], v183 offset:32768
	ds_read_b128 v[22:25], v183 offset:45056
	ds_read_b128 v[56:59], v184 offset:32768
	ds_read_b128 v[68:71], v184 offset:45056
	s_waitcnt lgkmcnt(3)
	v_mfma_f32_32x32x16_bf16 v[34:49], v[18:21], v[128:131], 0
	v_bitop3_b32 v66, v52, v60, v50 bitop3:0xde
	v_bitop3_b32 v52, v53, v55, v50 bitop3:0xde
	v_add_u32_e32 v185, 0, v52
	v_bitop3_b32 v52, v54, v55, v50 bitop3:0xde
	v_add_u32_e32 v186, 0, v52
	v_bitop3_b32 v67, v53, v60, v50 bitop3:0xde
	v_mov_b64_e32 v[2:3], s[68:69]
	s_waitcnt lgkmcnt(2)
	v_mfma_f32_32x32x16_bf16 v[18:33], v[22:25], v[128:131], 0
	v_mov_b64_e32 v[4:5], s[70:71]
	v_mov_b64_e32 v[6:7], s[72:73]
	v_mov_b64_e32 v[8:9], s[74:75]
	v_mov_b64_e32 v[10:11], s[76:77]
	v_mov_b64_e32 v[12:13], s[78:79]
	v_mov_b64_e32 v[14:15], s[80:81]
	v_mov_b64_e32 v[16:17], s[82:83]
	s_waitcnt lgkmcnt(1)
	v_mfma_f32_32x32x16_bf16 v[34:49], v[56:59], v[124:127], v[34:49]
	ds_read_b128 v[56:59], v185 offset:32768
	s_movk_i32 s82, 0x100
	ds_read_b128 v[74:77], v192
	v_bitop3_b32 v65, v62, v60, v50 bitop3:0xde
	v_readlane_b32 s80, v254, 41
	v_readlane_b32 s74, v254, 44
	v_readlane_b32 s81, v254, 42
	s_waitcnt lgkmcnt(2)
	v_mfma_f32_32x32x16_bf16 v[18:33], v[68:71], v[124:127], v[18:33]
	ds_read_b128 v[68:71], v185 offset:45056
	v_add_u32_e32 v226, 0, v65
	v_readlane_b32 s75, v254, 45
	v_readlane_b32 s83, v254, 43
	s_movk_i32 s81, 0x300
	v_add_u32_e32 v225, 0, v66
	v_add_u32_e32 v224, 0, v67
	s_waitcnt lgkmcnt(2)
	v_mfma_f32_32x32x16_bf16 v[34:49], v[56:59], v[120:123], v[34:49]
	ds_read_b128 v[56:59], v186 offset:32768
	s_waitcnt lgkmcnt(1)
	v_mfma_f32_32x32x16_bf16 v[18:33], v[68:71], v[120:123], v[18:33]
	v_bitop3_b32 v68, v54, v60, v50 bitop3:0xde
	ds_read_b128 v[52:55], v186 offset:45056
	v_add_u32_e32 v223, 0, v68
	s_waitcnt lgkmcnt(1)
	v_mfma_f32_32x32x16_bf16 v[34:49], v[56:59], v[116:119], v[34:49]
	v_bitop3_b32 v56, v62, v50, s0 bitop3:0x36
	v_add_u32_e32 v69, v56, v60
	s_movk_i32 s0, 0xa0
	v_add_u32_e32 v222, 0, v69
	s_waitcnt lgkmcnt(0)
	v_mfma_f32_32x32x16_bf16 v[18:33], v[52:55], v[116:119], v[18:33]
	v_mad_u32_u24 v52, v172, s18, v56
	v_add_u32_e32 v187, 0, v52
	ds_read_b128 v[52:55], v187 offset:32768
	ds_read_b128 v[56:59], v187 offset:45056
	s_waitcnt lgkmcnt(0)
	v_mfma_f32_32x32x16_bf16 v[18:33], v[56:59], v[112:115], v[18:33]
	v_bitop3_b32 v56, v62, v50, s0 bitop3:0x36
	v_add_u32_e32 v70, v56, v60
	s_movk_i32 s0, 0xc0
	v_add_u32_e32 v221, 0, v70
	v_mfma_f32_32x32x16_bf16 v[34:49], v[52:55], v[112:115], v[34:49]
	v_mad_u32_u24 v52, v172, s18, v56
	v_add_u32_e32 v188, 0, v52
	ds_read_b128 v[52:55], v188 offset:32768
	ds_read_b128 v[56:59], v188 offset:45056
	s_waitcnt lgkmcnt(0)
	v_mfma_f32_32x32x16_bf16 v[18:33], v[56:59], v[108:111], v[18:33]
	v_bitop3_b32 v56, v62, v50, s0 bitop3:0x36
	v_add_u32_e32 v71, v56, v60
	s_movk_i32 s0, 0xe0
	v_add_u32_e32 v220, 0, v71
	v_mfma_f32_32x32x16_bf16 v[34:49], v[52:55], v[108:111], v[34:49]
	v_mad_u32_u24 v52, v172, s18, v56
	v_add_u32_e32 v189, 0, v52
	ds_read_b128 v[52:55], v189 offset:32768
	ds_read_b128 v[56:59], v189 offset:45056
	s_waitcnt lgkmcnt(0)
	v_mfma_f32_32x32x16_bf16 v[18:33], v[56:59], v[104:107], v[18:33]
	v_bitop3_b32 v56, v62, v50, s0 bitop3:0x36
	v_add_u32_e32 v72, v56, v60
	s_movk_i32 s0, 0x120
	v_bitop3_b32 v51, v62, v50, s0 bitop3:0x36
	s_movk_i32 s0, 0x140
	v_add_u32_e32 v219, 0, v72
	v_mfma_f32_32x32x16_bf16 v[34:49], v[52:55], v[104:107], v[34:49]
	v_mad_u32_u24 v52, v172, s18, v56
	v_add_u32_e32 v190, 0, v52
	ds_read_b128 v[52:55], v190 offset:32768
	ds_read_b128 v[56:59], v190 offset:45056
	s_waitcnt lgkmcnt(0)
	v_mfma_f32_32x32x16_bf16 v[18:33], v[56:59], v[100:103], v[18:33]
	v_bitop3_b32 v56, v62, v50, s82 bitop3:0x36
	v_add_u32_e32 v73, v56, v60
	v_add_u32_e32 v218, 0, v73
	v_mfma_f32_32x32x16_bf16 v[34:49], v[52:55], v[100:103], v[34:49]
	v_mad_u32_u24 v52, v172, s18, v56
	v_add_u32_e32 v191, 0, v52
	ds_read_b128 v[52:55], v191 offset:32768
	ds_read_b128 v[56:59], v191 offset:45056
	s_waitcnt lgkmcnt(1)
	v_mfma_f32_32x32x16_bf16 v[34:49], v[52:55], v[74:77], v[34:49]
	v_mad_u32_u24 v52, v172, s18, v51
	v_add_u32_e32 v194, 0, v52
	ds_read_b128 v[52:55], v194 offset:32768
	s_waitcnt lgkmcnt(1)
	v_mfma_f32_32x32x16_bf16 v[18:33], v[56:59], v[74:77], v[18:33]
	ds_read_b128 v[56:59], v194 offset:45056
	ds_read_b128 v[76:79], v176
	v_add_u32_e32 v74, v51, v60
	v_bitop3_b32 v51, v62, v50, s0 bitop3:0x36
	s_movk_i32 s0, 0x160
	v_bitop3_b32 v50, v62, v50, s0 bitop3:0x36
	v_add_u32_e32 v75, v51, v60
	v_add_u32_e32 v217, 0, v74
	s_waitcnt lgkmcnt(0)
	v_mfma_f32_32x32x16_bf16 v[34:49], v[52:55], v[76:79], v[34:49]
	v_mad_u32_u24 v52, v172, s18, v51
	v_add_u32_e32 v195, 0, v52
	ds_read_b128 v[52:55], v195 offset:32768
	v_mad_u32_u24 v51, v172, s18, v50
	v_add_u32_e32 v196, 0, v51
	v_add_u32_e32 v216, 0, v75
	v_mfma_f32_32x32x16_bf16 v[18:33], v[56:59], v[76:79], v[18:33]
	ds_read_b128 v[56:59], v195 offset:45056
	ds_read_b128 v[76:79], v177
	s_waitcnt lgkmcnt(0)
	v_mfma_f32_32x32x16_bf16 v[34:49], v[52:55], v[76:79], v[34:49]
	v_mfma_f32_32x32x16_bf16 v[18:33], v[56:59], v[76:79], v[18:33]
	ds_read_b128 v[54:57], v196 offset:32768
	v_add_u32_e32 v76, v50, v60
	ds_read_b128 v[50:53], v196 offset:45056
	ds_read_b128 v[58:61], v175
	v_add_u32_e32 v215, 0, v76
	s_waitcnt lgkmcnt(0)
	v_mfma_f32_32x32x16_bf16 v[34:49], v[54:57], v[58:61], v[34:49]
	v_mfma_f32_32x32x16_bf16 v[18:33], v[50:53], v[58:61], v[18:33]
	s_nop 10
	v_max_f32_e32 v50, v35, v35
	v_max_f32_e32 v51, v34, v34
	v_max_f32_e32 v50, v51, v50
	v_max3_f32 v50, v50, v36, v37
	v_max3_f32 v50, v50, v38, v39
	v_max3_f32 v50, v50, v40, v41
	v_max3_f32 v50, v50, v42, v43
	v_max3_f32 v50, v50, v44, v45
	v_max3_f32 v50, v50, v46, v47
	v_max3_f32 v50, v50, v48, v49
	v_max3_f32 v50, v50, v18, v19
	v_max3_f32 v50, v50, v20, v21
	v_max3_f32 v50, v50, v22, v23
	v_max3_f32 v50, v50, v24, v25
	v_max3_f32 v50, v50, v26, v27
	v_max3_f32 v50, v50, v28, v29
	v_max3_f32 v50, v50, v30, v31
	v_max3_f32 v50, v50, v32, v33
	v_mov_b32_e32 v51, v50
	s_nop 1
	v_permlane32_swap_b32_e32 v50, v51
	v_max_f32_e32 v51, v51, v51
	v_max_f32_e32 v50, v50, v50
	v_max_f32_e32 v50, v50, v51
	v_add_f32_e32 v51, 0x7149f2ca, v50
	v_max_f32_e32 v50, 0xf149f2ca, v50
	v_cmp_ge_f32_e32 vcc, s5, v51
	v_sub_f32_e32 v51, 0xf149f2ca, v50
	s_cmp_eq_u64 vcc, exec
	v_mul_f32_e32 v51, 0x3dd53b94, v51
	s_cselect_b64 vcc, -1, 0
	v_exp_f32_e32 v51, v51
	s_add_i32 s0, s12, 0x4040
	v_mov_b32_e32 v52, 0xf149f2ca
	s_ashr_i32 s1, s0, 31
	v_cndmask_b32_e32 v214, v50, v52, vcc
	s_lshl_b64 s[16:17], s[0:1], 10
	v_mul_f32_e32 v50, 0xbdd53b94, v214
	s_add_u32 s16, s9, s16
	v_cndmask_b32_e64 v213, v51, 1.0, vcc
	v_mov_b32_e32 v51, v50
	s_addc_u32 s17, s10, s17
	s_mul_hi_i32 s1, s0, 0x600
	s_mulk_i32 s0, 0x600
	v_fmamk_f32 v34, v34, 0x3dd53b94, v50
	v_fmamk_f32 v35, v35, 0x3dd53b94, v50
	v_fmamk_f32 v36, v36, 0x3dd53b94, v50
	v_fmamk_f32 v37, v37, 0x3dd53b94, v50
	v_fmac_f32_e32 v51, 0x3dd53b94, v49
	s_add_u32 s0, s2, s0
	v_pk_fma_f32 v[138:139], v[32:33], s[30:31], v[50:51] op_sel_hi:[1,0,0]
	v_pk_fma_f32 v[140:141], v[30:31], s[30:31], v[50:51] op_sel_hi:[1,0,0]
	v_pk_fma_f32 v[146:147], v[28:29], s[30:31], v[50:51] op_sel_hi:[1,0,0]
	v_pk_fma_f32 v[132:133], v[26:27], s[30:31], v[50:51] op_sel_hi:[1,0,0]
	v_pk_fma_f32 v[134:135], v[24:25], s[30:31], v[50:51] op_sel_hi:[1,0,0]
	v_pk_fma_f32 v[136:137], v[22:23], s[30:31], v[50:51] op_sel_hi:[1,0,0]
	v_pk_fma_f32 v[142:143], v[20:21], s[30:31], v[50:51] op_sel_hi:[1,0,0]
	v_pk_fma_f32 v[144:145], v[18:19], s[30:31], v[50:51] op_sel_hi:[1,0,0]
	v_exp_f32_e32 v153, v34
	v_exp_f32_e32 v154, v35
	v_exp_f32_e32 v230, v36
	v_exp_f32_e32 v231, v37
	s_addc_u32 s1, s8, s1
	v_fmamk_f32 v38, v38, 0x3dd53b94, v50
	v_fmamk_f32 v39, v39, 0x3dd53b94, v50
	v_fmamk_f32 v40, v40, 0x3dd53b94, v50
	v_fmamk_f32 v41, v41, 0x3dd53b94, v50
	v_fmamk_f32 v42, v42, 0x3dd53b94, v50
	v_fmamk_f32 v43, v43, 0x3dd53b94, v50
	v_fmamk_f32 v44, v44, 0x3dd53b94, v50
	v_fmamk_f32 v45, v45, 0x3dd53b94, v50
	v_fmamk_f32 v46, v46, 0x3dd53b94, v50
	v_fmamk_f32 v47, v47, 0x3dd53b94, v50
	v_fmamk_f32 v48, v48, 0x3dd53b94, v50
	v_exp_f32_e32 v232, v38
	v_exp_f32_e32 v233, v39
	v_exp_f32_e32 v155, v40
	v_exp_f32_e32 v229, v41
	v_exp_f32_e32 v151, v42
	v_exp_f32_e32 v156, v43
	v_exp_f32_e32 v157, v44
	v_exp_f32_e32 v158, v45
	v_exp_f32_e32 v148, v46
	v_exp_f32_e32 v149, v47
	v_exp_f32_e32 v150, v48
	v_exp_f32_e32 v159, v51
	s_addk_i32 s14, 0x4000
	v_add_u32_e32 v199, s14, v63
	v_mov_b64_e32 v[64:65], v[16:17]
	v_mov_b64_e32 v[48:49], v[16:17]
	v_mov_b64_e32 v[32:33], v[16:17]
	s_addk_i32 s12, 0x4080
	s_sub_i32 s13, s13, 64
	v_mov_b64_e32 v[62:63], v[14:15]
	v_mov_b64_e32 v[60:61], v[12:13]
	v_mov_b64_e32 v[58:59], v[10:11]
	v_mov_b64_e32 v[56:57], v[8:9]
	v_mov_b64_e32 v[54:55], v[6:7]
	v_mov_b64_e32 v[52:53], v[4:5]
	v_mov_b64_e32 v[50:51], v[2:3]
	v_mov_b64_e32 v[46:47], v[14:15]
	v_mov_b64_e32 v[44:45], v[12:13]
	v_mov_b64_e32 v[42:43], v[10:11]
	v_mov_b64_e32 v[40:41], v[8:9]
	v_mov_b64_e32 v[38:39], v[6:7]
	v_mov_b64_e32 v[36:37], v[4:5]
	v_mov_b64_e32 v[34:35], v[2:3]
	v_mov_b64_e32 v[30:31], v[14:15]
	v_mov_b64_e32 v[28:29], v[12:13]
	v_mov_b64_e32 v[26:27], v[10:11]
	v_mov_b64_e32 v[24:25], v[8:9]
	v_mov_b64_e32 v[22:23], v[6:7]
	v_mov_b64_e32 v[20:21], v[4:5]
	v_mov_b64_e32 v[18:19], v[2:3]
	s_mov_b32 s14, s16
	s_mov_b32 s15, s17
	s_waitcnt vmcnt(0) lgkmcnt(0)
	s_barrier
